# v25 + phase0: straight-line silu fill, straight-line wc LDS fill, pipelined cache-conversion loop (all bit-identical)
# speedup vs baseline: 1.0057x; 1.0057x over previous
.LBB0_1114:
	v_mov_b32_e32 v0, v218
	s_nop 0
	v_ashrrev_i32_e32 v2, 6, v0
	v_cmp_gt_i32_e32 vcc, 64, v2
	s_and_saveexec_b64 s[8:9], vcc
	s_cbranch_execz .LBB0_1119
	s_lshr_b32 s0, s44, 5
	s_bfe_u32 s10, s46, 0x20003
	s_and_b32 s12, s45, 0x1c0
	s_lshl_b32 s1, s0, 11
	s_lshl_b32 s11, s10, 9
	s_or_b32 s2, s1, s11
	s_lshl_b32 s1, s10, 12
	s_lshl_b32 s0, s0, 9
	v_add_u32_e32 v8, s12, v2
	s_add_i32 s10, s1, s0
	s_mov_b32 s11, s3
	v_ashrrev_i32_e32 v9, 31, v8
	v_lshl_add_u64 v[18:19], v[8:9], 0, s[10:11]
	v_readlane_b32 s10, v254, 24
	v_readlane_b32 s11, v254, 25
	v_and_b32_e32 v6, 63, v0
	v_lshl_add_u64 v[14:15], v[8:9], 0, s[2:3]
	v_readlane_b32 s12, v254, 17
	v_mov_b64_e32 v[8:9], s[10:11]
	s_movk_i32 s2, 0x300
	v_mul_u32_u24_e32 v0, 0x84, v6
	v_lshlrev_b32_e32 v3, 1, v2
	v_lshlrev_b64 v[10:11], 9, v[14:15]
	v_readlane_b32 s13, v254, 18
	v_mad_u64_u32 v[8:9], s[10:11], v18, s2, v[8:9]
	v_add_u32_e32 v22, -8, v2
	v_add3_u32 v23, v0, v3, 0
	v_lshl_add_u64 v[2:3], s[12:13], 0, v[10:11]
	v_readlane_b32 s12, v254, 22
	v_readlane_b32 s10, v254, 42
	v_readlane_b32 s64, v254, 1
	v_readlane_b32 s13, v254, 23
	v_readlane_b32 s11, v254, 43
	v_lshlrev_b64 v[12:13], 7, v[14:15]
	v_readlane_b32 s65, v254, 2
	v_readlane_b32 s66, v254, 3
	v_readlane_b32 s67, v254, 4
	v_readlane_b32 s68, v254, 5
	v_readlane_b32 s69, v254, 6
	v_readlane_b32 s70, v254, 7
	v_readlane_b32 s71, v254, 8
	v_readlane_b32 s72, v254, 9
	v_readlane_b32 s73, v254, 10
	v_readlane_b32 s74, v254, 11
	v_readlane_b32 s75, v254, 12
	v_readlane_b32 s76, v254, 13
	v_readlane_b32 s77, v254, 14
	v_readlane_b32 s78, v254, 15
	v_readlane_b32 s79, v254, 16
	v_lshlrev_b64 v[20:21], 10, v[14:15]
	v_lshl_add_u64 v[4:5], s[12:13], 0, v[10:11]
	v_lshl_add_u64 v[10:11], s[10:11], 0, v[10:11]
	v_lshl_add_u64 v[12:13], s[68:69], 0, v[12:13]
	v_lshl_add_u64 v[14:15], s[64:65], 0, v[20:21]
	v_readlane_b32 s10, v254, 44
	v_readlane_b32 s64, v254, 26
	v_mad_i32_i24 v9, v19, s2, v9
	v_lshlrev_b64 v[16:17], 9, v[18:19]
	v_readlane_b32 s11, v254, 45
	v_lshlrev_b64 v[18:19], 8, v[18:19]
	v_readlane_b32 s78, v254, 40
	v_readlane_b32 s79, v254, 41
	v_cmp_gt_u32_e64 s[0:1], 32, v6
	v_lshlrev_b32_e32 v0, 2, v6
	v_lshlrev_b32_e32 v6, 1, v6
	v_mov_b32_e32 v7, v1
	v_lshl_add_u64 v[16:17], s[10:11], 0, v[16:17]
	v_lshl_add_u64 v[18:19], s[24:25], 0, v[18:19]
	v_lshl_add_u64 v[20:21], s[78:79], 0, v[20:21]
	s_mov_b64 s[10:11], 0
	v_readlane_b32 s65, v254, 27
	v_readlane_b32 s66, v254, 28
	v_readlane_b32 s67, v254, 29
	v_readlane_b32 s68, v254, 30
	v_readlane_b32 s69, v254, 31
	v_readlane_b32 s70, v254, 32
	v_readlane_b32 s71, v254, 33
	v_readlane_b32 s72, v254, 34
	v_readlane_b32 s73, v254, 35
	v_readlane_b32 s74, v254, 36
	v_readlane_b32 s75, v254, 37
	v_readlane_b32 s76, v254, 38
	v_readlane_b32 s77, v254, 39
	v_lshl_add_u64 v[126:127], v[10:11], 0, v[0:1]
	v_lshl_add_u64 v[128:129], v[4:5], 0, v[0:1]
	v_lshl_add_u64 v[130:131], v[2:3], 0, v[0:1]
	v_lshl_add_u64 v[132:133], v[20:21], 0, v[0:1]
	v_lshl_add_u64 v[134:135], v[14:15], 0, v[0:1]
	v_lshl_add_u64 v[136:137], v[12:13], 0, v[0:1]
	global_load_dword v100, v[126:127], off offset:-256
	global_load_dword v101, v[126:127], off
	global_load_dword v102, v[128:129], off offset:-256
	global_load_dword v103, v[128:129], off
	global_load_dword v104, v[130:131], off offset:-256
	global_load_dword v105, v[130:131], off
	global_load_dword v106, v[132:133], off
	global_load_dword v107, v[134:135], off
	global_load_dword v108, v[132:133], off offset:256
	global_load_dword v109, v[134:135], off offset:256
	global_load_dword v110, v[132:133], off offset:512
	global_load_dword v111, v[134:135], off offset:512
	global_load_dword v112, v[132:133], off offset:768
	global_load_dword v113, v[134:135], off offset:768
	s_and_saveexec_b64 s[12:13], s[0:1]
	global_load_dword v114, v[136:137], off
	s_or_b64 exec, exec, s[12:13]
	s_branch .LBB0_1117

.LBB0_1117:
	v_add_u32_e32 v116, 8, v22
	v_cmp_lt_i32_e32 vcc, 55, v116
	v_mov_b32_e32 v117, 0x1000
	v_mov_b32_e32 v118, 0x2000
	v_mov_b32_e32 v119, 0x400
	v_mov_b32_e32 v121, 0
	v_mov_b32_e32 v123, 0
	v_mov_b32_e32 v125, 0
	v_cndmask_b32_e32 v120, v117, v121, vcc
	v_cndmask_b32_e32 v122, v118, v121, vcc
	v_cndmask_b32_e32 v124, v119, v121, vcc
	v_lshl_add_u64 v[126:127], v[10:11], 0, v[0:1]
	v_lshl_add_u64 v[128:129], v[4:5], 0, v[0:1]
	v_lshl_add_u64 v[130:131], v[2:3], 0, v[0:1]
	v_lshl_add_u64 v[132:133], v[20:21], 0, v[0:1]
	v_lshl_add_u64 v[134:135], v[14:15], 0, v[0:1]
	v_lshl_add_u64 v[136:137], v[12:13], 0, v[0:1]
	v_lshl_add_u64 v[126:127], v[126:127], 0, v[120:121]
	v_lshl_add_u64 v[128:129], v[128:129], 0, v[120:121]
	v_lshl_add_u64 v[130:131], v[130:131], 0, v[120:121]
	v_lshl_add_u64 v[132:133], v[132:133], 0, v[122:123]
	v_lshl_add_u64 v[134:135], v[134:135], 0, v[122:123]
	v_lshl_add_u64 v[136:137], v[136:137], 0, v[124:125]
	s_waitcnt vmcnt(0)
	v_mov_b32_e32 v30, v100
	v_mov_b32_e32 v31, v101
	v_mov_b32_e32 v32, v102
	v_mov_b32_e32 v33, v103
	v_mov_b32_e32 v34, v104
	v_mov_b32_e32 v35, v105
	v_mov_b32_e32 v36, v106
	v_mov_b32_e32 v37, v107
	v_mov_b32_e32 v38, v108
	v_mov_b32_e32 v39, v109
	v_mov_b32_e32 v40, v110
	v_mov_b32_e32 v41, v111
	v_mov_b32_e32 v42, v112
	v_mov_b32_e32 v43, v113
	v_mov_b32_e32 v115, v114
	global_load_dword v100, v[126:127], off offset:-256
	global_load_dword v101, v[126:127], off
	global_load_dword v102, v[128:129], off offset:-256
	global_load_dword v103, v[128:129], off
	global_load_dword v104, v[130:131], off offset:-256
	global_load_dword v105, v[130:131], off
	global_load_dword v106, v[132:133], off
	global_load_dword v107, v[134:135], off
	global_load_dword v108, v[132:133], off offset:256
	global_load_dword v109, v[134:135], off offset:256
	global_load_dword v110, v[132:133], off offset:512
	global_load_dword v111, v[134:135], off offset:512
	global_load_dword v112, v[132:133], off offset:768
	global_load_dword v113, v[134:135], off offset:768
	s_and_saveexec_b64 s[12:13], s[0:1]
	global_load_dword v114, v[136:137], off
	s_or_b64 exec, exec, s[12:13]
	v_lshl_add_u64 v[24:25], v[18:19], 0, v[6:7]
	s_mov_b32 s12, 0x19a80000
	v_add_co_u32_e32 v28, vcc, s12, v24
	s_mov_b32 s12, 0x1c680000
	s_nop 0
	v_addc_co_u32_e32 v29, vcc, 0, v25, vcc
	v_add_co_u32_e32 v24, vcc, s12, v24
	v_lshl_add_u64 v[26:27], v[16:17], 0, v[6:7]
	s_nop 0
	v_addc_co_u32_e32 v25, vcc, 0, v25, vcc
	v_cvt_pk_bf16_f32 v30, v30, s0
	v_cvt_pk_bf16_f32 v31, v31, s0
	v_cvt_pk_bf16_f32 v32, v32, s0
	v_cvt_pk_bf16_f32 v33, v33, s0
	v_cvt_pk_bf16_f32 v34, v34, s0
	v_cvt_pk_bf16_f32 v35, v35, s0
	v_cvt_pk_bf16_f32 v37, v37, s0
	v_cvt_pk_bf16_f32 v38, v38, s0
	v_cvt_pk_bf16_f32 v39, v39, s0
	v_cvt_pk_bf16_f32 v40, v40, s0
	v_cvt_pk_bf16_f32 v41, v41, s0
	v_cvt_pk_bf16_f32 v42, v42, s0
	v_cvt_pk_bf16_f32 v43, v43, s0
	v_cvt_pk_bf16_f32 v36, v36, s0
	global_store_short v[28:29], v30, off
	ds_write_b16 v23, v32
	global_store_short v[24:25], v34, off
	global_store_short v[28:29], v31, off offset:128
	ds_write_b16 v23, v33 offset:8448
	global_store_short v[24:25], v35, off offset:128
	global_store_short v[26:27], v36, off offset:-256
	ds_write_b16 v23, v37 offset:16896
	global_store_short v[26:27], v38, off offset:-128
	ds_write_b16 v23, v39 offset:25344
	global_store_short v[26:27], v40, off
	ds_write_b16 v23, v41 offset:33792
	global_store_short v[26:27], v42, off offset:128
	ds_write_b16 v23, v43 offset:42240
	s_and_saveexec_b64 s[12:13], s[0:1]
	s_cbranch_execz .LBB0_1116
	v_lshl_add_u64 v[24:25], v[8:9], 0, v[6:7]
	v_cvt_pk_bf16_f32 v26, v115, s0
	global_store_short v[24:25], v26, off offset:-384
	global_store_short v[24:25], v26, off offset:-192
	global_store_short v[24:25], v26, off
	global_store_short v[24:25], v26, off offset:192
	s_branch .LBB0_1116

.LBB0_1137:
	s_andn2_b64 vcc, exec, s[0:1]
	s_cbranch_vccnz .LBB0_1151
	v_mov_b32_e32 v14, v218
	s_movk_i32 s0, 0x2400
	s_nop 0
	v_cmp_gt_i32_e32 vcc, s0, v14
	s_and_saveexec_b64 s[0:1], vcc
	s_cbranch_execz .LBB0_1145
	v_lshl_add_u32 v4, v14, 2, 0
	s_mov_b64 s[8:9], 0
	v_mov_b32_e32 v5, v14
	v_lshlrev_b32_e32 v100, 2, v14
	v_mov_b32_e32 v101, 0
	v_readlane_b32 s10, v254, 7
	v_readlane_b32 s11, v254, 8
	s_nop 3
	v_lshl_add_u64 v[102:103], s[10:11], 0, v[100:101]
	v_readlane_b32 s10, v254, 30
	v_readlane_b32 s11, v254, 31
	global_load_dword v76, v[102:103], off
	global_load_dword v77, v[102:103], off offset:2048
	s_nop 1
	v_lshl_add_u64 v[102:103], s[10:11], 0, v[100:101]
	global_load_dword v78, v[102:103], off
	global_load_dword v79, v[102:103], off offset:2048
	v_add_co_u32_e32 v102, vcc, 0x1000, v102
	s_nop 1
	v_addc_co_u32_e32 v103, vcc, 0, v103, vcc
	global_load_dword v80, v[102:103], off
	global_load_dword v81, v[102:103], off offset:2048
	v_add_co_u32_e32 v102, vcc, 0x1000, v102
	s_nop 1
	v_addc_co_u32_e32 v103, vcc, 0, v103, vcc
	global_load_dword v82, v[102:103], off
	global_load_dword v83, v[102:103], off offset:2048
	v_add_co_u32_e32 v102, vcc, 0x1000, v102
	s_nop 1
	v_addc_co_u32_e32 v103, vcc, 0, v103, vcc
	global_load_dword v84, v[102:103], off
	global_load_dword v85, v[102:103], off offset:2048
	v_add_co_u32_e32 v102, vcc, 0x1000, v102
	s_nop 1
	v_addc_co_u32_e32 v103, vcc, 0, v103, vcc
	global_load_dword v86, v[102:103], off
	global_load_dword v87, v[102:103], off offset:2048
	v_add_co_u32_e32 v102, vcc, 0x1000, v102
	s_nop 1
	v_addc_co_u32_e32 v103, vcc, 0, v103, vcc
	global_load_dword v88, v[102:103], off
	global_load_dword v89, v[102:103], off offset:2048
	v_add_co_u32_e32 v102, vcc, 0x1000, v102
	s_nop 1
	v_addc_co_u32_e32 v103, vcc, 0, v103, vcc
	global_load_dword v90, v[102:103], off
	global_load_dword v91, v[102:103], off offset:2048
	v_add_co_u32_e32 v102, vcc, 0x1000, v102
	s_nop 1
	v_addc_co_u32_e32 v103, vcc, 0, v103, vcc
	global_load_dword v92, v[102:103], off
	global_load_dword v93, v[102:103], off offset:2048
	s_waitcnt vmcnt(17)
	v_mul_f32_e32 v2, 0xbfb8aa3b, v76
	v_exp_f32_e32 v2, v2
	s_nop 0
	v_add_f32_e32 v2, 1.0, v2
	v_div_scale_f32 v5, s[10:11], v2, v2, v76
	v_rcp_f32_e32 v6, v5
	v_div_scale_f32 v7, vcc, v76, v2, v76
	v_fma_f32 v8, -v5, v6, 1.0
	v_fmac_f32_e32 v6, v8, v6
	v_mul_f32_e32 v8, v7, v6
	v_fma_f32 v9, -v5, v8, v7
	v_fmac_f32_e32 v8, v9, v6
	v_fma_f32 v5, -v5, v8, v7
	v_div_fmas_f32 v5, v5, v6, v8
	v_div_fixup_f32 v0, v5, v2, v76
	ds_write_b32 v4, v0
	s_waitcnt vmcnt(16)
	v_mul_f32_e32 v2, 0xbfb8aa3b, v77
	v_exp_f32_e32 v2, v2
	s_nop 0
	v_add_f32_e32 v2, 1.0, v2
	v_div_scale_f32 v5, s[10:11], v2, v2, v77
	v_rcp_f32_e32 v6, v5
	v_div_scale_f32 v7, vcc, v77, v2, v77
	v_fma_f32 v8, -v5, v6, 1.0
	v_fmac_f32_e32 v6, v8, v6
	v_mul_f32_e32 v8, v7, v6
	v_fma_f32 v9, -v5, v8, v7
	v_fmac_f32_e32 v8, v9, v6
	v_fma_f32 v5, -v5, v8, v7
	v_div_fmas_f32 v5, v5, v6, v8
	v_div_fixup_f32 v0, v5, v2, v77
	ds_write_b32 v4, v0 offset:2048
	s_waitcnt vmcnt(15)
	v_mul_f32_e32 v2, 0xbfb8aa3b, v78
	v_exp_f32_e32 v2, v2
	s_nop 0
	v_add_f32_e32 v2, 1.0, v2
	v_div_scale_f32 v5, s[10:11], v2, v2, v78
	v_rcp_f32_e32 v6, v5
	v_div_scale_f32 v7, vcc, v78, v2, v78
	v_fma_f32 v8, -v5, v6, 1.0
	v_fmac_f32_e32 v6, v8, v6
	v_mul_f32_e32 v8, v7, v6
	v_fma_f32 v9, -v5, v8, v7
	v_fmac_f32_e32 v8, v9, v6
	v_fma_f32 v5, -v5, v8, v7
	v_div_fmas_f32 v5, v5, v6, v8
	v_div_fixup_f32 v0, v5, v2, v78
	ds_write_b32 v4, v0 offset:4096
	s_waitcnt vmcnt(14)
	v_mul_f32_e32 v2, 0xbfb8aa3b, v79
	v_exp_f32_e32 v2, v2
	s_nop 0
	v_add_f32_e32 v2, 1.0, v2
	v_div_scale_f32 v5, s[10:11], v2, v2, v79
	v_rcp_f32_e32 v6, v5
	v_div_scale_f32 v7, vcc, v79, v2, v79
	v_fma_f32 v8, -v5, v6, 1.0
	v_fmac_f32_e32 v6, v8, v6
	v_mul_f32_e32 v8, v7, v6
	v_fma_f32 v9, -v5, v8, v7
	v_fmac_f32_e32 v8, v9, v6
	v_fma_f32 v5, -v5, v8, v7
	v_div_fmas_f32 v5, v5, v6, v8
	v_div_fixup_f32 v0, v5, v2, v79
	ds_write_b32 v4, v0 offset:6144
	s_waitcnt vmcnt(13)
	v_mul_f32_e32 v2, 0xbfb8aa3b, v80
	v_exp_f32_e32 v2, v2
	s_nop 0
	v_add_f32_e32 v2, 1.0, v2
	v_div_scale_f32 v5, s[10:11], v2, v2, v80
	v_rcp_f32_e32 v6, v5
	v_div_scale_f32 v7, vcc, v80, v2, v80
	v_fma_f32 v8, -v5, v6, 1.0
	v_fmac_f32_e32 v6, v8, v6
	v_mul_f32_e32 v8, v7, v6
	v_fma_f32 v9, -v5, v8, v7
	v_fmac_f32_e32 v8, v9, v6
	v_fma_f32 v5, -v5, v8, v7
	v_div_fmas_f32 v5, v5, v6, v8
	v_div_fixup_f32 v0, v5, v2, v80
	ds_write_b32 v4, v0 offset:8192
	s_waitcnt vmcnt(12)
	v_mul_f32_e32 v2, 0xbfb8aa3b, v81
	v_exp_f32_e32 v2, v2
	s_nop 0
	v_add_f32_e32 v2, 1.0, v2
	v_div_scale_f32 v5, s[10:11], v2, v2, v81
	v_rcp_f32_e32 v6, v5
	v_div_scale_f32 v7, vcc, v81, v2, v81
	v_fma_f32 v8, -v5, v6, 1.0
	v_fmac_f32_e32 v6, v8, v6
	v_mul_f32_e32 v8, v7, v6
	v_fma_f32 v9, -v5, v8, v7
	v_fmac_f32_e32 v8, v9, v6
	v_fma_f32 v5, -v5, v8, v7
	v_div_fmas_f32 v5, v5, v6, v8
	v_div_fixup_f32 v0, v5, v2, v81
	ds_write_b32 v4, v0 offset:10240
	s_waitcnt vmcnt(11)
	v_mul_f32_e32 v2, 0xbfb8aa3b, v82
	v_exp_f32_e32 v2, v2
	s_nop 0
	v_add_f32_e32 v2, 1.0, v2
	v_div_scale_f32 v5, s[10:11], v2, v2, v82
	v_rcp_f32_e32 v6, v5
	v_div_scale_f32 v7, vcc, v82, v2, v82
	v_fma_f32 v8, -v5, v6, 1.0
	v_fmac_f32_e32 v6, v8, v6
	v_mul_f32_e32 v8, v7, v6
	v_fma_f32 v9, -v5, v8, v7
	v_fmac_f32_e32 v8, v9, v6
	v_fma_f32 v5, -v5, v8, v7
	v_div_fmas_f32 v5, v5, v6, v8
	v_div_fixup_f32 v0, v5, v2, v82
	ds_write_b32 v4, v0 offset:12288
	s_waitcnt vmcnt(10)
	v_mul_f32_e32 v2, 0xbfb8aa3b, v83
	v_exp_f32_e32 v2, v2
	s_nop 0
	v_add_f32_e32 v2, 1.0, v2
	v_div_scale_f32 v5, s[10:11], v2, v2, v83
	v_rcp_f32_e32 v6, v5
	v_div_scale_f32 v7, vcc, v83, v2, v83
	v_fma_f32 v8, -v5, v6, 1.0
	v_fmac_f32_e32 v6, v8, v6
	v_mul_f32_e32 v8, v7, v6
	v_fma_f32 v9, -v5, v8, v7
	v_fmac_f32_e32 v8, v9, v6
	v_fma_f32 v5, -v5, v8, v7
	v_div_fmas_f32 v5, v5, v6, v8
	v_div_fixup_f32 v0, v5, v2, v83
	ds_write_b32 v4, v0 offset:14336
	s_waitcnt vmcnt(9)
	v_mul_f32_e32 v2, 0xbfb8aa3b, v84
	v_exp_f32_e32 v2, v2
	s_nop 0
	v_add_f32_e32 v2, 1.0, v2
	v_div_scale_f32 v5, s[10:11], v2, v2, v84
	v_rcp_f32_e32 v6, v5
	v_div_scale_f32 v7, vcc, v84, v2, v84
	v_fma_f32 v8, -v5, v6, 1.0
	v_fmac_f32_e32 v6, v8, v6
	v_mul_f32_e32 v8, v7, v6
	v_fma_f32 v9, -v5, v8, v7
	v_fmac_f32_e32 v8, v9, v6
	v_fma_f32 v5, -v5, v8, v7
	v_div_fmas_f32 v5, v5, v6, v8
	v_div_fixup_f32 v0, v5, v2, v84
	ds_write_b32 v4, v0 offset:16384
	s_waitcnt vmcnt(8)
	v_mul_f32_e32 v2, 0xbfb8aa3b, v85
	v_exp_f32_e32 v2, v2
	s_nop 0
	v_add_f32_e32 v2, 1.0, v2
	v_div_scale_f32 v5, s[10:11], v2, v2, v85
	v_rcp_f32_e32 v6, v5
	v_div_scale_f32 v7, vcc, v85, v2, v85
	v_fma_f32 v8, -v5, v6, 1.0
	v_fmac_f32_e32 v6, v8, v6
	v_mul_f32_e32 v8, v7, v6
	v_fma_f32 v9, -v5, v8, v7
	v_fmac_f32_e32 v8, v9, v6
	v_fma_f32 v5, -v5, v8, v7
	v_div_fmas_f32 v5, v5, v6, v8
	v_div_fixup_f32 v0, v5, v2, v85
	ds_write_b32 v4, v0 offset:18432
	s_waitcnt vmcnt(7)
	v_mul_f32_e32 v2, 0xbfb8aa3b, v86
	v_exp_f32_e32 v2, v2
	s_nop 0
	v_add_f32_e32 v2, 1.0, v2
	v_div_scale_f32 v5, s[10:11], v2, v2, v86
	v_rcp_f32_e32 v6, v5
	v_div_scale_f32 v7, vcc, v86, v2, v86
	v_fma_f32 v8, -v5, v6, 1.0
	v_fmac_f32_e32 v6, v8, v6
	v_mul_f32_e32 v8, v7, v6
	v_fma_f32 v9, -v5, v8, v7
	v_fmac_f32_e32 v8, v9, v6
	v_fma_f32 v5, -v5, v8, v7
	v_div_fmas_f32 v5, v5, v6, v8
	v_div_fixup_f32 v0, v5, v2, v86
	ds_write_b32 v4, v0 offset:20480
	s_waitcnt vmcnt(6)
	v_mul_f32_e32 v2, 0xbfb8aa3b, v87
	v_exp_f32_e32 v2, v2
	s_nop 0
	v_add_f32_e32 v2, 1.0, v2
	v_div_scale_f32 v5, s[10:11], v2, v2, v87
	v_rcp_f32_e32 v6, v5
	v_div_scale_f32 v7, vcc, v87, v2, v87
	v_fma_f32 v8, -v5, v6, 1.0
	v_fmac_f32_e32 v6, v8, v6
	v_mul_f32_e32 v8, v7, v6
	v_fma_f32 v9, -v5, v8, v7
	v_fmac_f32_e32 v8, v9, v6
	v_fma_f32 v5, -v5, v8, v7
	v_div_fmas_f32 v5, v5, v6, v8
	v_div_fixup_f32 v0, v5, v2, v87
	ds_write_b32 v4, v0 offset:22528
	s_waitcnt vmcnt(5)
	v_mul_f32_e32 v2, 0xbfb8aa3b, v88
	v_exp_f32_e32 v2, v2
	s_nop 0
	v_add_f32_e32 v2, 1.0, v2
	v_div_scale_f32 v5, s[10:11], v2, v2, v88
	v_rcp_f32_e32 v6, v5
	v_div_scale_f32 v7, vcc, v88, v2, v88
	v_fma_f32 v8, -v5, v6, 1.0
	v_fmac_f32_e32 v6, v8, v6
	v_mul_f32_e32 v8, v7, v6
	v_fma_f32 v9, -v5, v8, v7
	v_fmac_f32_e32 v8, v9, v6
	v_fma_f32 v5, -v5, v8, v7
	v_div_fmas_f32 v5, v5, v6, v8
	v_div_fixup_f32 v0, v5, v2, v88
	ds_write_b32 v4, v0 offset:24576
	s_waitcnt vmcnt(4)
	v_mul_f32_e32 v2, 0xbfb8aa3b, v89
	v_exp_f32_e32 v2, v2
	s_nop 0
	v_add_f32_e32 v2, 1.0, v2
	v_div_scale_f32 v5, s[10:11], v2, v2, v89
	v_rcp_f32_e32 v6, v5
	v_div_scale_f32 v7, vcc, v89, v2, v89
	v_fma_f32 v8, -v5, v6, 1.0
	v_fmac_f32_e32 v6, v8, v6
	v_mul_f32_e32 v8, v7, v6
	v_fma_f32 v9, -v5, v8, v7
	v_fmac_f32_e32 v8, v9, v6
	v_fma_f32 v5, -v5, v8, v7
	v_div_fmas_f32 v5, v5, v6, v8
	v_div_fixup_f32 v0, v5, v2, v89
	ds_write_b32 v4, v0 offset:26624
	s_waitcnt vmcnt(3)
	v_mul_f32_e32 v2, 0xbfb8aa3b, v90
	v_exp_f32_e32 v2, v2
	s_nop 0
	v_add_f32_e32 v2, 1.0, v2
	v_div_scale_f32 v5, s[10:11], v2, v2, v90
	v_rcp_f32_e32 v6, v5
	v_div_scale_f32 v7, vcc, v90, v2, v90
	v_fma_f32 v8, -v5, v6, 1.0
	v_fmac_f32_e32 v6, v8, v6
	v_mul_f32_e32 v8, v7, v6
	v_fma_f32 v9, -v5, v8, v7
	v_fmac_f32_e32 v8, v9, v6
	v_fma_f32 v5, -v5, v8, v7
	v_div_fmas_f32 v5, v5, v6, v8
	v_div_fixup_f32 v0, v5, v2, v90
	ds_write_b32 v4, v0 offset:28672
	s_waitcnt vmcnt(2)
	v_mul_f32_e32 v2, 0xbfb8aa3b, v91
	v_exp_f32_e32 v2, v2
	s_nop 0
	v_add_f32_e32 v2, 1.0, v2
	v_div_scale_f32 v5, s[10:11], v2, v2, v91
	v_rcp_f32_e32 v6, v5
	v_div_scale_f32 v7, vcc, v91, v2, v91
	v_fma_f32 v8, -v5, v6, 1.0
	v_fmac_f32_e32 v6, v8, v6
	v_mul_f32_e32 v8, v7, v6
	v_fma_f32 v9, -v5, v8, v7
	v_fmac_f32_e32 v8, v9, v6
	v_fma_f32 v5, -v5, v8, v7
	v_div_fmas_f32 v5, v5, v6, v8
	v_div_fixup_f32 v0, v5, v2, v91
	ds_write_b32 v4, v0 offset:30720
	s_waitcnt vmcnt(1)
	v_mul_f32_e32 v2, 0xbfb8aa3b, v92
	v_exp_f32_e32 v2, v2
	s_nop 0
	v_add_f32_e32 v2, 1.0, v2
	v_div_scale_f32 v5, s[10:11], v2, v2, v92
	v_rcp_f32_e32 v6, v5
	v_div_scale_f32 v7, vcc, v92, v2, v92
	v_fma_f32 v8, -v5, v6, 1.0
	v_fmac_f32_e32 v6, v8, v6
	v_mul_f32_e32 v8, v7, v6
	v_fma_f32 v9, -v5, v8, v7
	v_fmac_f32_e32 v8, v9, v6
	v_fma_f32 v5, -v5, v8, v7
	v_div_fmas_f32 v5, v5, v6, v8
	v_div_fixup_f32 v0, v5, v2, v92
	ds_write_b32 v4, v0 offset:32768
	s_waitcnt vmcnt(0)
	v_mul_f32_e32 v2, 0xbfb8aa3b, v93
	v_exp_f32_e32 v2, v2
	s_nop 0
	v_add_f32_e32 v2, 1.0, v2
	v_div_scale_f32 v5, s[10:11], v2, v2, v93
	v_rcp_f32_e32 v6, v5
	v_div_scale_f32 v7, vcc, v93, v2, v93
	v_fma_f32 v8, -v5, v6, 1.0
	v_fmac_f32_e32 v6, v8, v6
	v_mul_f32_e32 v8, v7, v6
	v_fma_f32 v9, -v5, v8, v7
	v_fmac_f32_e32 v8, v9, v6
	v_fma_f32 v5, -v5, v8, v7
	v_div_fmas_f32 v5, v5, v6, v8
	v_div_fixup_f32 v0, v5, v2, v93
	ds_write_b32 v4, v0 offset:34816

.LBB0_1152:
	s_andn2_b64 vcc, exec, s[0:1]
	s_cbranch_vccnz .LBB0_1076
	v_mov_b32_e32 v3, v218
	s_ashr_i32 s0, s46, 5
	s_lshl_b32 s1, s46, 5
	s_movk_i32 s8, 0x1c00
	s_and_b32 s18, s1, 0x3e0
	s_ashr_i32 s1, s0, 31
	v_cmp_gt_i32_e32 vcc, s8, v3
	s_and_saveexec_b64 s[8:9], vcc
	s_cbranch_execz .LBB0_1160
	s_mul_i32 s10, s0, 0x1980000
	v_readlane_b32 s64, v251, 25
	s_mul_hi_i32 s11, s0, 0x1980000
	v_readlane_b32 s65, v251, 26
	s_add_u32 s10, s64, s10
	s_mul_i32 s12, s0, 0xc0
	s_addc_u32 s11, s65, s11
	s_ashr_i32 s13, s12, 31
	v_lshl_add_u32 v6, v3, 2, 0
	s_mov_b64 s[14:15], 0
	v_mov_b32_e32 v2, v3
	v_readlane_b32 s66, v251, 27
	v_readlane_b32 s67, v251, 28
	v_readlane_b32 s68, v251, 29
	v_readlane_b32 s69, v251, 30
	v_readlane_b32 s70, v251, 31
	v_readlane_b32 s71, v251, 32
	v_readlane_b32 s72, v251, 33
	v_readlane_b32 s73, v251, 34
	v_readlane_b32 s74, v251, 35
	v_readlane_b32 s75, v251, 36
	v_readlane_b32 s76, v251, 37
	v_readlane_b32 s77, v251, 38
	v_readlane_b32 s78, v251, 39
	v_readlane_b32 s79, v251, 40
	v_readlane_b32 s74, v255, 1
	v_readlane_b32 s75, v255, 2
	v_mov_b32_e32 v133, 0
	v_mov_b32_e32 v135, 0
	v_mov_b32_e32 v138, 0x1400
	v_mov_b32_e32 v139, 0x2000
	v_mov_b32_e32 v136, v3
	s_mov_b32 s16, 0x92492493
	v_mul_hi_i32 v137, v136, s16
	v_add_u32_e32 v137, v137, v136
	v_lshrrev_b32_e32 v140, 31, v137
	v_ashrrev_i32_e32 v137, 7, v137
	v_add_u32_e32 v137, v137, v140
	v_mul_u32_u24_e32 v140, 0xe0, v137
	v_sub_u32_e32 v104, v136, v140
	v_lshl_add_u32 v118, v137, 9, v6
	v_add_u32_e32 v137, s18, v137
	v_mul_u32_u24_e32 v132, 0x6600, v137
	v_cmp_lt_i32_e32 vcc, 31, v104
	v_subrev_u32_e32 v140, 32, v104
	v_max_i32_e32 v134, 0, v140
	v_cndmask_b32_e32 v140, v138, v139, vcc
	v_lshl_add_u32 v140, v104, 2, v140
	v_add_u32_e32 v132, v132, v140
	v_add_u32_e32 v134, s12, v134
	v_lshl_add_u64 v[140:141], s[10:11], 0, v[132:133]
	global_load_dword v76, v[140:141], off
	v_lshl_add_u64 v[140:141], v[134:135], 2, s[74:75]
	global_load_dword v90, v[140:141], off
	v_add_u32_e32 v136, 512, v3
	s_mov_b32 s16, 0x92492493
	v_mul_hi_i32 v137, v136, s16
	v_add_u32_e32 v137, v137, v136
	v_lshrrev_b32_e32 v140, 31, v137
	v_ashrrev_i32_e32 v137, 7, v137
	v_add_u32_e32 v137, v137, v140
	v_mul_u32_u24_e32 v140, 0xe0, v137
	v_sub_u32_e32 v105, v136, v140
	v_lshl_add_u32 v119, v137, 9, v6
	v_add_u32_e32 v137, s18, v137
	v_mul_u32_u24_e32 v132, 0x6600, v137
	v_cmp_lt_i32_e32 vcc, 31, v105
	v_subrev_u32_e32 v140, 32, v105
	v_max_i32_e32 v134, 0, v140
	v_cndmask_b32_e32 v140, v138, v139, vcc
	v_lshl_add_u32 v140, v105, 2, v140
	v_add_u32_e32 v132, v132, v140
	v_add_u32_e32 v134, s12, v134
	v_lshl_add_u64 v[140:141], s[10:11], 0, v[132:133]
	global_load_dword v77, v[140:141], off
	v_lshl_add_u64 v[140:141], v[134:135], 2, s[74:75]
	global_load_dword v91, v[140:141], off
	v_add_u32_e32 v136, 1024, v3
	s_mov_b32 s16, 0x92492493
	v_mul_hi_i32 v137, v136, s16
	v_add_u32_e32 v137, v137, v136
	v_lshrrev_b32_e32 v140, 31, v137
	v_ashrrev_i32_e32 v137, 7, v137
	v_add_u32_e32 v137, v137, v140
	v_mul_u32_u24_e32 v140, 0xe0, v137
	v_sub_u32_e32 v106, v136, v140
	v_lshl_add_u32 v120, v137, 9, v6
	v_add_u32_e32 v137, s18, v137
	v_mul_u32_u24_e32 v132, 0x6600, v137
	v_cmp_lt_i32_e32 vcc, 31, v106
	v_subrev_u32_e32 v140, 32, v106
	v_max_i32_e32 v134, 0, v140
	v_cndmask_b32_e32 v140, v138, v139, vcc
	v_lshl_add_u32 v140, v106, 2, v140
	v_add_u32_e32 v132, v132, v140
	v_add_u32_e32 v134, s12, v134
	v_lshl_add_u64 v[140:141], s[10:11], 0, v[132:133]
	global_load_dword v78, v[140:141], off
	v_lshl_add_u64 v[140:141], v[134:135], 2, s[74:75]
	global_load_dword v92, v[140:141], off
	v_add_u32_e32 v136, 1536, v3
	s_mov_b32 s16, 0x92492493
	v_mul_hi_i32 v137, v136, s16
	v_add_u32_e32 v137, v137, v136
	v_lshrrev_b32_e32 v140, 31, v137
	v_ashrrev_i32_e32 v137, 7, v137
	v_add_u32_e32 v137, v137, v140
	v_mul_u32_u24_e32 v140, 0xe0, v137
	v_sub_u32_e32 v107, v136, v140
	v_lshl_add_u32 v121, v137, 9, v6
	v_add_u32_e32 v137, s18, v137
	v_mul_u32_u24_e32 v132, 0x6600, v137
	v_cmp_lt_i32_e32 vcc, 31, v107
	v_subrev_u32_e32 v140, 32, v107
	v_max_i32_e32 v134, 0, v140
	v_cndmask_b32_e32 v140, v138, v139, vcc
	v_lshl_add_u32 v140, v107, 2, v140
	v_add_u32_e32 v132, v132, v140
	v_add_u32_e32 v134, s12, v134
	v_lshl_add_u64 v[140:141], s[10:11], 0, v[132:133]
	global_load_dword v79, v[140:141], off
	v_lshl_add_u64 v[140:141], v[134:135], 2, s[74:75]
	global_load_dword v93, v[140:141], off
	v_add_u32_e32 v136, 2048, v3
	s_mov_b32 s16, 0x92492493
	v_mul_hi_i32 v137, v136, s16
	v_add_u32_e32 v137, v137, v136
	v_lshrrev_b32_e32 v140, 31, v137
	v_ashrrev_i32_e32 v137, 7, v137
	v_add_u32_e32 v137, v137, v140
	v_mul_u32_u24_e32 v140, 0xe0, v137
	v_sub_u32_e32 v108, v136, v140
	v_lshl_add_u32 v122, v137, 9, v6
	v_add_u32_e32 v137, s18, v137
	v_mul_u32_u24_e32 v132, 0x6600, v137
	v_cmp_lt_i32_e32 vcc, 31, v108
	v_subrev_u32_e32 v140, 32, v108
	v_max_i32_e32 v134, 0, v140
	v_cndmask_b32_e32 v140, v138, v139, vcc
	v_lshl_add_u32 v140, v108, 2, v140
	v_add_u32_e32 v132, v132, v140
	v_add_u32_e32 v134, s12, v134
	v_lshl_add_u64 v[140:141], s[10:11], 0, v[132:133]
	global_load_dword v80, v[140:141], off
	v_lshl_add_u64 v[140:141], v[134:135], 2, s[74:75]
	global_load_dword v94, v[140:141], off
	v_add_u32_e32 v136, 2560, v3
	s_mov_b32 s16, 0x92492493
	v_mul_hi_i32 v137, v136, s16
	v_add_u32_e32 v137, v137, v136
	v_lshrrev_b32_e32 v140, 31, v137
	v_ashrrev_i32_e32 v137, 7, v137
	v_add_u32_e32 v137, v137, v140
	v_mul_u32_u24_e32 v140, 0xe0, v137
	v_sub_u32_e32 v109, v136, v140
	v_lshl_add_u32 v123, v137, 9, v6
	v_add_u32_e32 v137, s18, v137
	v_mul_u32_u24_e32 v132, 0x6600, v137
	v_cmp_lt_i32_e32 vcc, 31, v109
	v_subrev_u32_e32 v140, 32, v109
	v_max_i32_e32 v134, 0, v140
	v_cndmask_b32_e32 v140, v138, v139, vcc
	v_lshl_add_u32 v140, v109, 2, v140
	v_add_u32_e32 v132, v132, v140
	v_add_u32_e32 v134, s12, v134
	v_lshl_add_u64 v[140:141], s[10:11], 0, v[132:133]
	global_load_dword v81, v[140:141], off
	v_lshl_add_u64 v[140:141], v[134:135], 2, s[74:75]
	global_load_dword v95, v[140:141], off
	v_add_u32_e32 v136, 3072, v3
	s_mov_b32 s16, 0x92492493
	v_mul_hi_i32 v137, v136, s16
	v_add_u32_e32 v137, v137, v136
	v_lshrrev_b32_e32 v140, 31, v137
	v_ashrrev_i32_e32 v137, 7, v137
	v_add_u32_e32 v137, v137, v140
	v_mul_u32_u24_e32 v140, 0xe0, v137
	v_sub_u32_e32 v110, v136, v140
	v_lshl_add_u32 v124, v137, 9, v6
	v_add_u32_e32 v137, s18, v137
	v_mul_u32_u24_e32 v132, 0x6600, v137
	v_cmp_lt_i32_e32 vcc, 31, v110
	v_subrev_u32_e32 v140, 32, v110
	v_max_i32_e32 v134, 0, v140
	v_cndmask_b32_e32 v140, v138, v139, vcc
	v_lshl_add_u32 v140, v110, 2, v140
	v_add_u32_e32 v132, v132, v140
	v_add_u32_e32 v134, s12, v134
	v_lshl_add_u64 v[140:141], s[10:11], 0, v[132:133]
	global_load_dword v82, v[140:141], off
	v_lshl_add_u64 v[140:141], v[134:135], 2, s[74:75]
	global_load_dword v96, v[140:141], off
	v_add_u32_e32 v136, 3584, v3
	s_mov_b32 s16, 0x92492493
	v_mul_hi_i32 v137, v136, s16
	v_add_u32_e32 v137, v137, v136
	v_lshrrev_b32_e32 v140, 31, v137
	v_ashrrev_i32_e32 v137, 7, v137
	v_add_u32_e32 v137, v137, v140
	v_mul_u32_u24_e32 v140, 0xe0, v137
	v_sub_u32_e32 v111, v136, v140
	v_lshl_add_u32 v125, v137, 9, v6
	v_add_u32_e32 v137, s18, v137
	v_mul_u32_u24_e32 v132, 0x6600, v137
	v_cmp_lt_i32_e32 vcc, 31, v111
	v_subrev_u32_e32 v140, 32, v111
	v_max_i32_e32 v134, 0, v140
	v_cndmask_b32_e32 v140, v138, v139, vcc
	v_lshl_add_u32 v140, v111, 2, v140
	v_add_u32_e32 v132, v132, v140
	v_add_u32_e32 v134, s12, v134
	v_lshl_add_u64 v[140:141], s[10:11], 0, v[132:133]
	global_load_dword v83, v[140:141], off
	v_lshl_add_u64 v[140:141], v[134:135], 2, s[74:75]
	global_load_dword v97, v[140:141], off
	v_add_u32_e32 v136, 4096, v3
	s_mov_b32 s16, 0x92492493
	v_mul_hi_i32 v137, v136, s16
	v_add_u32_e32 v137, v137, v136
	v_lshrrev_b32_e32 v140, 31, v137
	v_ashrrev_i32_e32 v137, 7, v137
	v_add_u32_e32 v137, v137, v140
	v_mul_u32_u24_e32 v140, 0xe0, v137
	v_sub_u32_e32 v112, v136, v140
	v_lshl_add_u32 v126, v137, 9, v6
	v_add_u32_e32 v137, s18, v137
	v_mul_u32_u24_e32 v132, 0x6600, v137
	v_cmp_lt_i32_e32 vcc, 31, v112
	v_subrev_u32_e32 v140, 32, v112
	v_max_i32_e32 v134, 0, v140
	v_cndmask_b32_e32 v140, v138, v139, vcc
	v_lshl_add_u32 v140, v112, 2, v140
	v_add_u32_e32 v132, v132, v140
	v_add_u32_e32 v134, s12, v134
	v_lshl_add_u64 v[140:141], s[10:11], 0, v[132:133]
	global_load_dword v84, v[140:141], off
	v_lshl_add_u64 v[140:141], v[134:135], 2, s[74:75]
	global_load_dword v98, v[140:141], off
	v_add_u32_e32 v136, 4608, v3
	s_mov_b32 s16, 0x92492493
	v_mul_hi_i32 v137, v136, s16
	v_add_u32_e32 v137, v137, v136
	v_lshrrev_b32_e32 v140, 31, v137
	v_ashrrev_i32_e32 v137, 7, v137
	v_add_u32_e32 v137, v137, v140
	v_mul_u32_u24_e32 v140, 0xe0, v137
	v_sub_u32_e32 v113, v136, v140
	v_lshl_add_u32 v127, v137, 9, v6
	v_add_u32_e32 v137, s18, v137
	v_mul_u32_u24_e32 v132, 0x6600, v137
	v_cmp_lt_i32_e32 vcc, 31, v113
	v_subrev_u32_e32 v140, 32, v113
	v_max_i32_e32 v134, 0, v140
	v_cndmask_b32_e32 v140, v138, v139, vcc
	v_lshl_add_u32 v140, v113, 2, v140
	v_add_u32_e32 v132, v132, v140
	v_add_u32_e32 v134, s12, v134
	v_lshl_add_u64 v[140:141], s[10:11], 0, v[132:133]
	global_load_dword v85, v[140:141], off
	v_lshl_add_u64 v[140:141], v[134:135], 2, s[74:75]
	global_load_dword v99, v[140:141], off
	v_add_u32_e32 v136, 5120, v3
	s_mov_b32 s16, 0x92492493
	v_mul_hi_i32 v137, v136, s16
	v_add_u32_e32 v137, v137, v136
	v_lshrrev_b32_e32 v140, 31, v137
	v_ashrrev_i32_e32 v137, 7, v137
	v_add_u32_e32 v137, v137, v140
	v_mul_u32_u24_e32 v140, 0xe0, v137
	v_sub_u32_e32 v114, v136, v140
	v_lshl_add_u32 v128, v137, 9, v6
	v_add_u32_e32 v137, s18, v137
	v_mul_u32_u24_e32 v132, 0x6600, v137
	v_cmp_lt_i32_e32 vcc, 31, v114
	v_subrev_u32_e32 v140, 32, v114
	v_max_i32_e32 v134, 0, v140
	v_cndmask_b32_e32 v140, v138, v139, vcc
	v_lshl_add_u32 v140, v114, 2, v140
	v_add_u32_e32 v132, v132, v140
	v_add_u32_e32 v134, s12, v134
	v_lshl_add_u64 v[140:141], s[10:11], 0, v[132:133]
	global_load_dword v86, v[140:141], off
	v_lshl_add_u64 v[140:141], v[134:135], 2, s[74:75]
	global_load_dword v100, v[140:141], off
	v_add_u32_e32 v136, 5632, v3
	s_mov_b32 s16, 0x92492493
	v_mul_hi_i32 v137, v136, s16
	v_add_u32_e32 v137, v137, v136
	v_lshrrev_b32_e32 v140, 31, v137
	v_ashrrev_i32_e32 v137, 7, v137
	v_add_u32_e32 v137, v137, v140
	v_mul_u32_u24_e32 v140, 0xe0, v137
	v_sub_u32_e32 v115, v136, v140
	v_lshl_add_u32 v129, v137, 9, v6
	v_add_u32_e32 v137, s18, v137
	v_mul_u32_u24_e32 v132, 0x6600, v137
	v_cmp_lt_i32_e32 vcc, 31, v115
	v_subrev_u32_e32 v140, 32, v115
	v_max_i32_e32 v134, 0, v140
	v_cndmask_b32_e32 v140, v138, v139, vcc
	v_lshl_add_u32 v140, v115, 2, v140
	v_add_u32_e32 v132, v132, v140
	v_add_u32_e32 v134, s12, v134
	v_lshl_add_u64 v[140:141], s[10:11], 0, v[132:133]
	global_load_dword v87, v[140:141], off
	v_lshl_add_u64 v[140:141], v[134:135], 2, s[74:75]
	global_load_dword v101, v[140:141], off
	v_add_u32_e32 v136, 6144, v3
	s_mov_b32 s16, 0x92492493
	v_mul_hi_i32 v137, v136, s16
	v_add_u32_e32 v137, v137, v136
	v_lshrrev_b32_e32 v140, 31, v137
	v_ashrrev_i32_e32 v137, 7, v137
	v_add_u32_e32 v137, v137, v140
	v_mul_u32_u24_e32 v140, 0xe0, v137
	v_sub_u32_e32 v116, v136, v140
	v_lshl_add_u32 v130, v137, 9, v6
	v_add_u32_e32 v137, s18, v137
	v_mul_u32_u24_e32 v132, 0x6600, v137
	v_cmp_lt_i32_e32 vcc, 31, v116
	v_subrev_u32_e32 v140, 32, v116
	v_max_i32_e32 v134, 0, v140
	v_cndmask_b32_e32 v140, v138, v139, vcc
	v_lshl_add_u32 v140, v116, 2, v140
	v_add_u32_e32 v132, v132, v140
	v_add_u32_e32 v134, s12, v134
	v_lshl_add_u64 v[140:141], s[10:11], 0, v[132:133]
	global_load_dword v88, v[140:141], off
	v_lshl_add_u64 v[140:141], v[134:135], 2, s[74:75]
	global_load_dword v102, v[140:141], off
	v_add_u32_e32 v136, 6656, v3
	s_mov_b32 s16, 0x92492493
	v_mul_hi_i32 v137, v136, s16
	v_add_u32_e32 v137, v137, v136
	v_lshrrev_b32_e32 v140, 31, v137
	v_ashrrev_i32_e32 v137, 7, v137
	v_add_u32_e32 v137, v137, v140
	v_mul_u32_u24_e32 v140, 0xe0, v137
	v_sub_u32_e32 v117, v136, v140
	v_lshl_add_u32 v131, v137, 9, v6
	v_add_u32_e32 v137, s18, v137
	v_mul_u32_u24_e32 v132, 0x6600, v137
	v_cmp_lt_i32_e32 vcc, 31, v117
	v_subrev_u32_e32 v140, 32, v117
	v_max_i32_e32 v134, 0, v140
	v_cndmask_b32_e32 v140, v138, v139, vcc
	v_lshl_add_u32 v140, v117, 2, v140
	v_add_u32_e32 v132, v132, v140
	v_add_u32_e32 v134, s12, v134
	v_lshl_add_u64 v[140:141], s[10:11], 0, v[132:133]
	global_load_dword v89, v[140:141], off
	v_lshl_add_u64 v[140:141], v[134:135], 2, s[74:75]
	global_load_dword v103, v[140:141], off
	s_waitcnt vmcnt(26)
	v_cmp_lt_i32_e32 vcc, 31, v104
	v_mul_f32_e32 v140, v76, v90
	s_nop 0
	v_cndmask_b32_e32 v140, v76, v140, vcc
	ds_write_b32 v118, v140
	s_waitcnt vmcnt(24)
	v_cmp_lt_i32_e32 vcc, 31, v105
	v_mul_f32_e32 v140, v77, v91
	s_nop 0
	v_cndmask_b32_e32 v140, v77, v140, vcc
	ds_write_b32 v119, v140 offset:2048
	s_waitcnt vmcnt(22)
	v_cmp_lt_i32_e32 vcc, 31, v106
	v_mul_f32_e32 v140, v78, v92
	s_nop 0
	v_cndmask_b32_e32 v140, v78, v140, vcc
	ds_write_b32 v120, v140 offset:4096
	s_waitcnt vmcnt(20)
	v_cmp_lt_i32_e32 vcc, 31, v107
	v_mul_f32_e32 v140, v79, v93
	s_nop 0
	v_cndmask_b32_e32 v140, v79, v140, vcc
	ds_write_b32 v121, v140 offset:6144
	s_waitcnt vmcnt(18)
	v_cmp_lt_i32_e32 vcc, 31, v108
	v_mul_f32_e32 v140, v80, v94
	s_nop 0
	v_cndmask_b32_e32 v140, v80, v140, vcc
	ds_write_b32 v122, v140 offset:8192
	s_waitcnt vmcnt(16)
	v_cmp_lt_i32_e32 vcc, 31, v109
	v_mul_f32_e32 v140, v81, v95
	s_nop 0
	v_cndmask_b32_e32 v140, v81, v140, vcc
	ds_write_b32 v123, v140 offset:10240
	s_waitcnt vmcnt(14)
	v_cmp_lt_i32_e32 vcc, 31, v110
	v_mul_f32_e32 v140, v82, v96
	s_nop 0
	v_cndmask_b32_e32 v140, v82, v140, vcc
	ds_write_b32 v124, v140 offset:12288
	s_waitcnt vmcnt(12)
	v_cmp_lt_i32_e32 vcc, 31, v111
	v_mul_f32_e32 v140, v83, v97
	s_nop 0
	v_cndmask_b32_e32 v140, v83, v140, vcc
	ds_write_b32 v125, v140 offset:14336
	s_waitcnt vmcnt(10)
	v_cmp_lt_i32_e32 vcc, 31, v112
	v_mul_f32_e32 v140, v84, v98
	s_nop 0
	v_cndmask_b32_e32 v140, v84, v140, vcc
	ds_write_b32 v126, v140 offset:16384
	s_waitcnt vmcnt(8)
	v_cmp_lt_i32_e32 vcc, 31, v113
	v_mul_f32_e32 v140, v85, v99
	s_nop 0
	v_cndmask_b32_e32 v140, v85, v140, vcc
	ds_write_b32 v127, v140 offset:18432
	s_waitcnt vmcnt(6)
	v_cmp_lt_i32_e32 vcc, 31, v114
	v_mul_f32_e32 v140, v86, v100
	s_nop 0
	v_cndmask_b32_e32 v140, v86, v140, vcc
	ds_write_b32 v128, v140 offset:20480
	s_waitcnt vmcnt(4)
	v_cmp_lt_i32_e32 vcc, 31, v115
	v_mul_f32_e32 v140, v87, v101
	s_nop 0
	v_cndmask_b32_e32 v140, v87, v140, vcc
	ds_write_b32 v129, v140 offset:22528
	s_waitcnt vmcnt(2)
	v_cmp_lt_i32_e32 vcc, 31, v116
	v_mul_f32_e32 v140, v88, v102
	s_nop 0
	v_cndmask_b32_e32 v140, v88, v140, vcc
	ds_write_b32 v130, v140 offset:24576
	s_waitcnt vmcnt(0)
	v_cmp_lt_i32_e32 vcc, 31, v117
	v_mul_f32_e32 v140, v89, v103
	s_nop 0
	v_cndmask_b32_e32 v140, v89, v140, vcc
	ds_write_b32 v131, v140 offset:26624
